# scan helper waves: raw r/k/v/a/u loads addressed as scalar base + lane offset + immediate (no per-load 64-bit vector address arithmetic)
# speedup vs baseline: 1.0281x; 1.0064x over previous
.LBB0_1337:
	s_cmpk_eq_i32 s58, 0xff
	s_mov_b64 s[6:7], -1
	s_waitcnt lgkmcnt(0)
	s_barrier
	s_cbranch_scc1 .LBB0_1357
	s_cmpk_lt_u32 s58, 0xfe
	s_cbranch_scc0 .Lhelper_noload
	s_add_u32 s62, s12, 0x21000
	s_addc_u32 s63, s13, 0
	s_add_u32 s64, s12, 0x23000
	s_addc_u32 s65, s13, 0
	s_add_u32 s66, s14, 0x8c61000
	s_addc_u32 s67, s15, 0
	s_add_u32 s68, s14, 0x8c63000
	s_addc_u32 s69, s15, 0
	s_add_u32 s70, s14, 0x8c65000
	s_addc_u32 s71, s15, 0
	s_add_u32 s72, s14, 0x8c67000
	s_addc_u32 s73, s15, 0
	s_add_u32 s74, s14, 0x8c69000
	s_addc_u32 s75, s15, 0
	s_add_u32 s76, s14, 0x8c6b000
	s_addc_u32 s77, s15, 0
	s_add_u32 s78, s36, 0x14c21000
	s_addc_u32 s79, s37, 0
	s_add_u32 s80, s36, 0x14c23000
	s_addc_u32 s81, s37, 0
	global_load_ushort v84, v22, s[66:67] offset:-4096
	global_load_ushort v85, v22, s[66:67] offset:-2048
	global_load_ushort v101, v22, s[66:67]
	global_load_ushort v102, v22, s[66:67] offset:2048
	global_load_ushort v103, v22, s[62:63] offset:-4096
	global_load_ushort v104, v22, s[62:63] offset:-2048
	global_load_ushort v105, v22, s[68:69] offset:-4096
	global_load_ushort v106, v22, s[68:69] offset:-2048
	global_load_ushort v107, v22, s[68:69]
	global_load_ushort v108, v22, s[68:69] offset:2048
	global_load_ushort v109, v22, s[70:71] offset:-4096
	global_load_ushort v110, v22, s[70:71] offset:-2048
	global_load_ushort v111, v22, s[62:63]
	global_load_ushort v112, v22, s[62:63] offset:2048
	global_load_ushort v113, v22, s[78:79]
	global_load_ushort v114, v22, s[78:79] offset:2048
	global_load_ushort v115, v22, s[70:71]
	global_load_ushort v116, v22, s[70:71] offset:2048
	global_load_ushort v117, v22, s[72:73] offset:-4096
	global_load_ushort v118, v22, s[72:73] offset:-2048
	global_load_ushort v119, v22, s[72:73]
	global_load_ushort v120, v22, s[72:73] offset:2048
	global_load_ushort v121, v22, s[74:75] offset:-4096
	global_load_ushort v122, v22, s[74:75] offset:-2048
	global_load_ushort v68, v22, s[74:75]
	global_load_ushort v70, v22, s[74:75] offset:2048
	global_load_ushort v123, v22, s[76:77] offset:-4096
	global_load_ushort v69, v22, s[76:77] offset:-2048
	global_load_ushort v71, v22, s[76:77]
	global_load_ushort v124, v22, s[64:65] offset:-4096
	global_load_ushort v80, v22, s[64:65] offset:-2048
	global_load_ushort v74, v22, s[76:77] offset:2048
	global_load_ushort v81, v22, s[64:65]
	global_load_ushort v125, v22, s[64:65] offset:2048
	global_load_ushort v126, v22, s[80:81]
	global_load_ushort v127, v22, s[80:81] offset:2048
	global_load_ushort v128, v22, s[80:81] offset:-4096
	global_load_ushort v82, v22, s[80:81] offset:-2048
	global_load_ushort v129, v22, s[78:79] offset:-4096
	global_load_ushort v130, v22, s[78:79] offset:-2048
